# grid barrier: XCD leaders no longer publish the now-unread per-XCD generation (removes one atomic + its ack wait from the leader path)
# baseline (speedup 1.0000x reference)
; DI unsigned xb_ld(unsigned* p) { return __hip_atomic_load(p, __ATOMIC_RELAXED, __HIP_MEMORY_SCOPE_AGENT); }
; DI unsigned xb_add(unsigned* p, unsigned v) { return __hip_atomic_fetch_add(p, v, __ATOMIC_RELAXED, __HIP_MEMORY_SCOPE_AGENT); }
; #define XB_SPIN(cond, bar) do { unsigned _sp = 0; while (cond) { \
;     if ((++_sp & 255u) == 0u) { if (xb_ld(&(bar)[XB_TMO])) break; if (_sp > XB_SPIN_CAP) { atomicAdd(&(bar)[XB_TMO], 1u); break; } } } } while (0)
; DI void xcd_barrier(const XcdBarrier& b) {
;     ...
;       __builtin_amdgcn_fence(__ATOMIC_RELEASE, "agent");
;       asm volatile("s_waitcnt vmcnt(0)" ::: "memory");
;       const unsigned og = xb_add(&bar[XB_TOP], 1u);
;       const unsigned tg = og / nx;
;       if (og + 1u == (tg + 1u) * nx) xb_add(&bar[XB_TOPGEN], 1u);
;       else XB_SPIN(xb_ld(&bar[XB_TOPGEN]) == tg, bar);
;       __builtin_amdgcn_fence(__ATOMIC_ACQUIRE, "agent");
;       xb_add(&bar[XB_XGEN(b.x)], 1u);
;       asm volatile("s_waitcnt vmcnt(0)" ::: "memory");
.LBB0_350:
	s_or_b64 exec, exec, s[34:35]
	s_mov_b64 s[34:35], exec
	v_mbcnt_lo_u32_b32 v0, s34, 0
	v_mbcnt_hi_u32_b32 v0, s35, v0
	v_cmp_eq_u32_e32 vcc, 0, v0
	s_waitcnt vmcnt(0)
	buffer_inv sc1
	s_and_saveexec_b64 s[38:39], vcc
	s_cbranch_execz .LBB0_352
	s_bcnt1_i32_b64 s2, s[34:35]
	v_readlane_b32 s8, v253, 58
	v_mov_b32_e32 v0, s2
	v_readlane_b32 s9, v253, 59
	s_nop 4
.LBB0_352:
	s_or_b64 exec, exec, s[38:39]
	s_waitcnt vmcnt(0)

; DI unsigned xb_ld(unsigned* p) { return __hip_atomic_load(p, __ATOMIC_RELAXED, __HIP_MEMORY_SCOPE_AGENT); }
; DI unsigned xb_add(unsigned* p, unsigned v) { return __hip_atomic_fetch_add(p, v, __ATOMIC_RELAXED, __HIP_MEMORY_SCOPE_AGENT); }
; #define XB_SPIN(cond, bar) do { unsigned _sp = 0; while (cond) { \
;     if ((++_sp & 255u) == 0u) { if (xb_ld(&(bar)[XB_TMO])) break; if (_sp > XB_SPIN_CAP) { atomicAdd(&(bar)[XB_TMO], 1u); break; } } } } while (0)
; DI void xcd_barrier(const XcdBarrier& b) {
;     ...
;       __builtin_amdgcn_fence(__ATOMIC_RELEASE, "agent");
;       asm volatile("s_waitcnt vmcnt(0)" ::: "memory");
;       const unsigned og = xb_add(&bar[XB_TOP], 1u);
;       const unsigned tg = og / nx;
;       if (og + 1u == (tg + 1u) * nx) xb_add(&bar[XB_TOPGEN], 1u);
;       else XB_SPIN(xb_ld(&bar[XB_TOPGEN]) == tg, bar);
;       __builtin_amdgcn_fence(__ATOMIC_ACQUIRE, "agent");
;       xb_add(&bar[XB_XGEN(b.x)], 1u);
;       asm volatile("s_waitcnt vmcnt(0)" ::: "memory");
.LBB0_457:
	s_or_b64 exec, exec, s[34:35]
	s_mov_b64 s[34:35], exec
	v_mbcnt_lo_u32_b32 v0, s34, 0
	v_mbcnt_hi_u32_b32 v0, s35, v0
	v_cmp_eq_u32_e32 vcc, 0, v0
	s_waitcnt vmcnt(0)
	buffer_inv sc1
	s_and_saveexec_b64 s[40:41], vcc
	s_cbranch_execz .LBB0_459
	s_bcnt1_i32_b64 s8, s[34:35]
	v_mov_b32_e32 v0, s8
	v_readlane_b32 s8, v253, 58
	v_readlane_b32 s9, v253, 59
	s_nop 4
.LBB0_459:
	s_or_b64 exec, exec, s[40:41]
	s_waitcnt vmcnt(0)

; DI unsigned xb_ld(unsigned* p) { return __hip_atomic_load(p, __ATOMIC_RELAXED, __HIP_MEMORY_SCOPE_AGENT); }
; DI unsigned xb_add(unsigned* p, unsigned v) { return __hip_atomic_fetch_add(p, v, __ATOMIC_RELAXED, __HIP_MEMORY_SCOPE_AGENT); }
; #define XB_SPIN(cond, bar) do { unsigned _sp = 0; while (cond) { \
;     if ((++_sp & 255u) == 0u) { if (xb_ld(&(bar)[XB_TMO])) break; if (_sp > XB_SPIN_CAP) { atomicAdd(&(bar)[XB_TMO], 1u); break; } } } } while (0)
; DI void xcd_barrier(const XcdBarrier& b) {
;     ...
;       __builtin_amdgcn_fence(__ATOMIC_RELEASE, "agent");
;       asm volatile("s_waitcnt vmcnt(0)" ::: "memory");
;       const unsigned og = xb_add(&bar[XB_TOP], 1u);
;       const unsigned tg = og / nx;
;       if (og + 1u == (tg + 1u) * nx) xb_add(&bar[XB_TOPGEN], 1u);
;       else XB_SPIN(xb_ld(&bar[XB_TOPGEN]) == tg, bar);
;       __builtin_amdgcn_fence(__ATOMIC_ACQUIRE, "agent");
;       xb_add(&bar[XB_XGEN(b.x)], 1u);
;       asm volatile("s_waitcnt vmcnt(0)" ::: "memory");
.LBB0_543:
	s_or_b64 exec, exec, s[34:35]
	s_mov_b64 s[34:35], exec
	v_mbcnt_lo_u32_b32 v0, s34, 0
	v_mbcnt_hi_u32_b32 v0, s35, v0
	v_cmp_eq_u32_e32 vcc, 0, v0
	s_waitcnt vmcnt(0)
	buffer_inv sc1
	s_and_saveexec_b64 s[40:41], vcc
	s_cbranch_execz .LBB0_545
	s_bcnt1_i32_b64 s8, s[34:35]
	v_mov_b32_e32 v0, s8
	v_readlane_b32 s8, v253, 58
	v_readlane_b32 s9, v253, 59
	s_nop 4
.LBB0_545:
	s_or_b64 exec, exec, s[40:41]
	s_waitcnt vmcnt(0)

; DI unsigned xb_ld(unsigned* p) { return __hip_atomic_load(p, __ATOMIC_RELAXED, __HIP_MEMORY_SCOPE_AGENT); }
; DI unsigned xb_add(unsigned* p, unsigned v) { return __hip_atomic_fetch_add(p, v, __ATOMIC_RELAXED, __HIP_MEMORY_SCOPE_AGENT); }
; #define XB_SPIN(cond, bar) do { unsigned _sp = 0; while (cond) { \
;     if ((++_sp & 255u) == 0u) { if (xb_ld(&(bar)[XB_TMO])) break; if (_sp > XB_SPIN_CAP) { atomicAdd(&(bar)[XB_TMO], 1u); break; } } } } while (0)
; DI void xcd_barrier(const XcdBarrier& b) {
;     ...
;       __builtin_amdgcn_fence(__ATOMIC_RELEASE, "agent");
;       asm volatile("s_waitcnt vmcnt(0)" ::: "memory");
;       const unsigned og = xb_add(&bar[XB_TOP], 1u);
;       const unsigned tg = og / nx;
;       if (og + 1u == (tg + 1u) * nx) xb_add(&bar[XB_TOPGEN], 1u);
;       else XB_SPIN(xb_ld(&bar[XB_TOPGEN]) == tg, bar);
;       __builtin_amdgcn_fence(__ATOMIC_ACQUIRE, "agent");
;       xb_add(&bar[XB_XGEN(b.x)], 1u);
;       asm volatile("s_waitcnt vmcnt(0)" ::: "memory");
.LBB0_655:
	s_or_b64 exec, exec, s[34:35]
	s_mov_b64 s[34:35], exec
	v_mbcnt_lo_u32_b32 v0, s34, 0
	v_mbcnt_hi_u32_b32 v0, s35, v0
	v_cmp_eq_u32_e32 vcc, 0, v0
	s_waitcnt vmcnt(0)
	buffer_inv sc1
	s_and_saveexec_b64 s[38:39], vcc
	s_cbranch_execz .LBB0_657
	s_bcnt1_i32_b64 s8, s[34:35]
	v_mov_b32_e32 v0, s8
	v_readlane_b32 s8, v253, 58
	v_readlane_b32 s9, v253, 59
	s_nop 4
.LBB0_657:
	s_or_b64 exec, exec, s[38:39]
	s_waitcnt vmcnt(0)

; DI unsigned xb_ld(unsigned* p) { return __hip_atomic_load(p, __ATOMIC_RELAXED, __HIP_MEMORY_SCOPE_AGENT); }
; DI unsigned xb_add(unsigned* p, unsigned v) { return __hip_atomic_fetch_add(p, v, __ATOMIC_RELAXED, __HIP_MEMORY_SCOPE_AGENT); }
; #define XB_SPIN(cond, bar) do { unsigned _sp = 0; while (cond) { \
;     if ((++_sp & 255u) == 0u) { if (xb_ld(&(bar)[XB_TMO])) break; if (_sp > XB_SPIN_CAP) { atomicAdd(&(bar)[XB_TMO], 1u); break; } } } } while (0)
; DI void xcd_barrier(const XcdBarrier& b) {
;     ...
;       __builtin_amdgcn_fence(__ATOMIC_RELEASE, "agent");
;       asm volatile("s_waitcnt vmcnt(0)" ::: "memory");
;       const unsigned og = xb_add(&bar[XB_TOP], 1u);
;       const unsigned tg = og / nx;
;       if (og + 1u == (tg + 1u) * nx) xb_add(&bar[XB_TOPGEN], 1u);
;       else XB_SPIN(xb_ld(&bar[XB_TOPGEN]) == tg, bar);
;       __builtin_amdgcn_fence(__ATOMIC_ACQUIRE, "agent");
;       xb_add(&bar[XB_XGEN(b.x)], 1u);
;       asm volatile("s_waitcnt vmcnt(0)" ::: "memory");
.LBB0_750:
	s_or_b64 exec, exec, s[34:35]
	s_mov_b64 s[34:35], exec
	v_mbcnt_lo_u32_b32 v0, s34, 0
	v_mbcnt_hi_u32_b32 v0, s35, v0
	v_cmp_eq_u32_e32 vcc, 0, v0
	s_waitcnt vmcnt(0)
	buffer_inv sc1
	s_and_saveexec_b64 s[38:39], vcc
	s_cbranch_execz .LBB0_752
	s_bcnt1_i32_b64 s2, s[34:35]
	v_readlane_b32 s8, v253, 58
	v_mov_b32_e32 v0, s2
	v_readlane_b32 s9, v253, 59
	s_nop 4
.LBB0_752:
	s_or_b64 exec, exec, s[38:39]
	s_waitcnt vmcnt(0)

; DI unsigned xb_ld(unsigned* p) { return __hip_atomic_load(p, __ATOMIC_RELAXED, __HIP_MEMORY_SCOPE_AGENT); }
; DI unsigned xb_add(unsigned* p, unsigned v) { return __hip_atomic_fetch_add(p, v, __ATOMIC_RELAXED, __HIP_MEMORY_SCOPE_AGENT); }
; #define XB_SPIN(cond, bar) do { unsigned _sp = 0; while (cond) { \
;     if ((++_sp & 255u) == 0u) { if (xb_ld(&(bar)[XB_TMO])) break; if (_sp > XB_SPIN_CAP) { atomicAdd(&(bar)[XB_TMO], 1u); break; } } } } while (0)
; DI void xcd_barrier(const XcdBarrier& b) {
;     ...
;       __builtin_amdgcn_fence(__ATOMIC_RELEASE, "agent");
;       asm volatile("s_waitcnt vmcnt(0)" ::: "memory");
;       const unsigned og = xb_add(&bar[XB_TOP], 1u);
;       const unsigned tg = og / nx;
;       if (og + 1u == (tg + 1u) * nx) xb_add(&bar[XB_TOPGEN], 1u);
;       else XB_SPIN(xb_ld(&bar[XB_TOPGEN]) == tg, bar);
;       __builtin_amdgcn_fence(__ATOMIC_ACQUIRE, "agent");
;       xb_add(&bar[XB_XGEN(b.x)], 1u);
;       asm volatile("s_waitcnt vmcnt(0)" ::: "memory");
.LBB0_840:
	s_or_b64 exec, exec, s[34:35]
	s_mov_b64 s[34:35], exec
	v_mbcnt_lo_u32_b32 v0, s34, 0
	v_mbcnt_hi_u32_b32 v0, s35, v0
	v_cmp_eq_u32_e32 vcc, 0, v0
	s_waitcnt vmcnt(0)
	buffer_inv sc1
	s_and_saveexec_b64 s[38:39], vcc
	s_cbranch_execz .LBB0_842
	s_bcnt1_i32_b64 s6, s[34:35]
	v_mov_b32_e32 v0, s6
	v_readlane_b32 s6, v253, 58
	v_readlane_b32 s7, v253, 59
	s_nop 4
.LBB0_842:
	s_or_b64 exec, exec, s[38:39]
	s_waitcnt vmcnt(0)

; DI unsigned xb_ld(unsigned* p) { return __hip_atomic_load(p, __ATOMIC_RELAXED, __HIP_MEMORY_SCOPE_AGENT); }
; DI unsigned xb_add(unsigned* p, unsigned v) { return __hip_atomic_fetch_add(p, v, __ATOMIC_RELAXED, __HIP_MEMORY_SCOPE_AGENT); }
; #define XB_SPIN(cond, bar) do { unsigned _sp = 0; while (cond) { \
;     if ((++_sp & 255u) == 0u) { if (xb_ld(&(bar)[XB_TMO])) break; if (_sp > XB_SPIN_CAP) { atomicAdd(&(bar)[XB_TMO], 1u); break; } } } } while (0)
; DI void xcd_barrier(const XcdBarrier& b) {
;     ...
;       __builtin_amdgcn_fence(__ATOMIC_RELEASE, "agent");
;       asm volatile("s_waitcnt vmcnt(0)" ::: "memory");
;       const unsigned og = xb_add(&bar[XB_TOP], 1u);
;       const unsigned tg = og / nx;
;       if (og + 1u == (tg + 1u) * nx) xb_add(&bar[XB_TOPGEN], 1u);
;       else XB_SPIN(xb_ld(&bar[XB_TOPGEN]) == tg, bar);
;       __builtin_amdgcn_fence(__ATOMIC_ACQUIRE, "agent");
;       xb_add(&bar[XB_XGEN(b.x)], 1u);
;       asm volatile("s_waitcnt vmcnt(0)" ::: "memory");
.LBB0_1025:
	s_or_b64 exec, exec, s[34:35]
	s_mov_b64 s[34:35], exec
	v_mbcnt_lo_u32_b32 v0, s34, 0
	v_mbcnt_hi_u32_b32 v0, s35, v0
	v_cmp_eq_u32_e32 vcc, 0, v0
	s_waitcnt vmcnt(0)
	buffer_inv sc1
	s_and_saveexec_b64 s[38:39], vcc
	s_cbranch_execz .LBB0_1027
	s_bcnt1_i32_b64 s2, s[34:35]
	v_readlane_b32 s8, v253, 58
	v_mov_b32_e32 v0, s2
	v_readlane_b32 s9, v253, 59
	s_nop 4
.LBB0_1027:
	s_or_b64 exec, exec, s[38:39]
	s_waitcnt vmcnt(0)

; DI unsigned xb_ld(unsigned* p) { return __hip_atomic_load(p, __ATOMIC_RELAXED, __HIP_MEMORY_SCOPE_AGENT); }
; DI unsigned xb_add(unsigned* p, unsigned v) { return __hip_atomic_fetch_add(p, v, __ATOMIC_RELAXED, __HIP_MEMORY_SCOPE_AGENT); }
; #define XB_SPIN(cond, bar) do { unsigned _sp = 0; while (cond) { \
;     if ((++_sp & 255u) == 0u) { if (xb_ld(&(bar)[XB_TMO])) break; if (_sp > XB_SPIN_CAP) { atomicAdd(&(bar)[XB_TMO], 1u); break; } } } } while (0)
; DI void xcd_barrier(const XcdBarrier& b) {
;     ...
;       __builtin_amdgcn_fence(__ATOMIC_RELEASE, "agent");
;       asm volatile("s_waitcnt vmcnt(0)" ::: "memory");
;       const unsigned og = xb_add(&bar[XB_TOP], 1u);
;       const unsigned tg = og / nx;
;       if (og + 1u == (tg + 1u) * nx) xb_add(&bar[XB_TOPGEN], 1u);
;       else XB_SPIN(xb_ld(&bar[XB_TOPGEN]) == tg, bar);
;       __builtin_amdgcn_fence(__ATOMIC_ACQUIRE, "agent");
;       xb_add(&bar[XB_XGEN(b.x)], 1u);
;       asm volatile("s_waitcnt vmcnt(0)" ::: "memory");
.LBB0_1111:
	s_or_b64 exec, exec, s[34:35]
	s_mov_b64 s[34:35], exec
	v_mbcnt_lo_u32_b32 v0, s34, 0
	v_mbcnt_hi_u32_b32 v0, s35, v0
	v_cmp_eq_u32_e32 vcc, 0, v0
	s_waitcnt vmcnt(0)
	buffer_inv sc1
	s_and_saveexec_b64 s[38:39], vcc
	s_cbranch_execz .LBB0_1113
	s_bcnt1_i32_b64 s2, s[34:35]
	v_readlane_b32 s8, v253, 58
	v_mov_b32_e32 v0, s2
	v_readlane_b32 s9, v253, 59
	s_nop 4
.LBB0_1113:
	s_or_b64 exec, exec, s[38:39]
	s_waitcnt vmcnt(0)

; DI unsigned xb_ld(unsigned* p) { return __hip_atomic_load(p, __ATOMIC_RELAXED, __HIP_MEMORY_SCOPE_AGENT); }
; DI unsigned xb_add(unsigned* p, unsigned v) { return __hip_atomic_fetch_add(p, v, __ATOMIC_RELAXED, __HIP_MEMORY_SCOPE_AGENT); }
; #define XB_SPIN(cond, bar) do { unsigned _sp = 0; while (cond) { \
;     if ((++_sp & 255u) == 0u) { if (xb_ld(&(bar)[XB_TMO])) break; if (_sp > XB_SPIN_CAP) { atomicAdd(&(bar)[XB_TMO], 1u); break; } } } } while (0)
; DI void xcd_barrier(const XcdBarrier& b) {
;     ...
;       __builtin_amdgcn_fence(__ATOMIC_RELEASE, "agent");
;       asm volatile("s_waitcnt vmcnt(0)" ::: "memory");
;       const unsigned og = xb_add(&bar[XB_TOP], 1u);
;       const unsigned tg = og / nx;
;       if (og + 1u == (tg + 1u) * nx) xb_add(&bar[XB_TOPGEN], 1u);
;       else XB_SPIN(xb_ld(&bar[XB_TOPGEN]) == tg, bar);
;       __builtin_amdgcn_fence(__ATOMIC_ACQUIRE, "agent");
;       xb_add(&bar[XB_XGEN(b.x)], 1u);
;       asm volatile("s_waitcnt vmcnt(0)" ::: "memory");
.LBB0_1191:
	s_or_b64 exec, exec, s[34:35]
	s_mov_b64 s[34:35], exec
	v_mbcnt_lo_u32_b32 v0, s34, 0
	v_mbcnt_hi_u32_b32 v0, s35, v0
	v_cmp_eq_u32_e32 vcc, 0, v0
	s_waitcnt vmcnt(0)
	buffer_inv sc1
	s_and_saveexec_b64 s[38:39], vcc
	s_cbranch_execz .LBB0_1193
	s_bcnt1_i32_b64 s2, s[34:35]
	v_readlane_b32 s6, v253, 58
	v_mov_b32_e32 v0, s2
	v_readlane_b32 s7, v253, 59
	s_nop 4
.LBB0_1193:
	s_or_b64 exec, exec, s[38:39]
	s_waitcnt vmcnt(0)
